# v4 + FF1 (relu^2) epilogue: touch-prefetch of the 7 later per-row sum-of-squares lines so the serialized row_rs loads hit L1
# baseline (speedup 1.0000x reference)
.LBB0_190:
	s_waitcnt lgkmcnt(0)
	v_cndmask_b32_e64 v131, 0, 1, s[46:47]
	v_mov_b32_e32 v130, 1.0
	v_cmp_ne_u32_e64 s[42:43], 1, v131
	s_andn2_b64 vcc, exec, s[46:47]
	v_ashrrev_i32_e32 v185, 31, v184
	v_mov_b32_e32 v136, 1.0
	s_cbranch_vccnz .LBB0_192
	v_lshlrev_b64 v[132:133], 7, v[184:185]
	v_lshl_add_u64 v[136:137], v[178:179], 0, v[132:133]
	v_add_co_u32_e32 v244, vcc, 0x1000, v136
	s_nop 1
	v_addc_co_u32_e32 v245, vcc, 0, v137, vcc
	v_add_co_u32_e32 v246, vcc, 0x4000, v136
	s_nop 1
	v_addc_co_u32_e32 v247, vcc, 0, v137, vcc
	v_add_co_u32_e32 v240, vcc, 0x5000, v136
	s_nop 1
	v_addc_co_u32_e32 v241, vcc, 0, v137, vcc
	global_load_dwordx4 v[132:135], v[136:137], off
	s_nop 0
	global_load_dwordx4 v[136:139], v[136:137], off offset:16
	global_load_dword v239, v[244:245], off offset:-2048
	global_load_dword v239, v[244:245], off
	global_load_dword v239, v[244:245], off offset:2048
	global_load_dword v239, v[246:247], off
	global_load_dword v239, v[246:247], off offset:2048
	global_load_dword v239, v[240:241], off
	global_load_dword v239, v[240:241], off offset:2048
	s_waitcnt vmcnt(7)
	v_mov_b32_e32 v140, v132
	v_mov_b32_e32 v141, v136
	v_mov_b32_e32 v136, v133
	v_pk_add_f32 v[132:133], v[140:141], v[136:137]
	v_mov_b32_e32 v136, v134
	v_mov_b32_e32 v137, v138
	v_mov_b32_e32 v138, v135
	v_pk_add_f32 v[134:135], v[136:137], v[138:139]
	s_nop 0
	v_pk_add_f32 v[132:133], v[132:133], v[134:135]
	s_nop 0
	v_add_f32_e32 v131, v132, v133
	v_and_b32_e32 v133, 64, v210
	v_xor_b32_e32 v132, 16, v210
	v_add_u32_e32 v133, 64, v133
	v_cmp_lt_i32_e32 vcc, v132, v133
	s_nop 1
	v_cndmask_b32_e32 v132, v210, v132, vcc
	v_lshlrev_b32_e32 v132, 2, v132
	ds_bpermute_b32 v132, v132, v131
	s_waitcnt lgkmcnt(0)
	v_add_f32_e32 v131, v131, v132
	v_xor_b32_e32 v132, 32, v210
	v_cmp_lt_i32_e32 vcc, v132, v133
	s_nop 1
	v_cndmask_b32_e32 v132, v210, v132, vcc
	v_lshlrev_b32_e32 v132, 2, v132
	ds_bpermute_b32 v132, v132, v131
	s_waitcnt lgkmcnt(0)
	v_add_f32_e32 v131, v131, v132
	v_fmamk_f32 v131, v131, 0x3a000000, v207
	v_cmp_gt_f32_e32 vcc, s91, v131
	v_mul_f32_e32 v132, 0x4f800000, v131
	s_nop 0
	v_cndmask_b32_e32 v131, v131, v132, vcc
	v_sqrt_f32_e32 v132, v131
	s_nop 0
	v_add_u32_e32 v133, -1, v132
	v_fma_f32 v134, -v133, v132, v131
	v_cmp_ge_f32_e64 s[0:1], 0, v134
	v_add_u32_e32 v134, 1, v132
	s_nop 0
	v_cndmask_b32_e64 v133, v132, v133, s[0:1]
	v_fma_f32 v132, -v134, v132, v131
	v_cmp_lt_f32_e64 s[0:1], 0, v132
	s_nop 1
	v_cndmask_b32_e64 v132, v133, v134, s[0:1]
	v_mul_f32_e32 v133, 0x37800000, v132
	v_cndmask_b32_e32 v132, v132, v133, vcc
	v_cmp_class_f32_e32 vcc, v131, v208
	s_nop 1
	v_cndmask_b32_e32 v131, v132, v131, vcc
	v_div_scale_f32 v132, s[0:1], v131, v131, 1.0
	v_rcp_f32_e32 v133, v132
	s_nop 0
	v_fma_f32 v134, -v132, v133, 1.0
	v_fmac_f32_e32 v133, v134, v133
	v_div_scale_f32 v134, vcc, 1.0, v131, 1.0
	v_mul_f32_e32 v135, v134, v133
	v_fma_f32 v136, -v132, v135, v134
	v_fmac_f32_e32 v135, v136, v133
	v_fma_f32 v132, -v132, v135, v134
	v_div_fmas_f32 v132, v132, v133, v135
	v_div_fixup_f32 v136, v132, v131, 1.0
